# spatial gating loop: gains hoisted, waits relaxed so prefetch stays in flight, LDS reads batched ahead of MFMAs
# speedup vs baseline: 1.0079x; 1.0046x over previous
.Lat_resc_back:
	s_cmpk_lt_u32 s35, 0x47
	s_waitcnt lgkmcnt(4)
	s_barrier
	s_cbranch_scc1 .Lat_loop
	s_waitcnt lgkmcnt(0)
	s_nop 7
	s_nop 7
	v_sub_f32_e32 v105, 0, v168
	v_mov_b32_e32 v98, v138
	s_branch .LBB0_105
.Ltr_1004:
	s_branch .LBB0_1004
.Ltr_19:
	s_branch .LBB0_19
.Ltr_20:
	s_branch .LBB0_20
.Ltr_21:
	s_branch .LBB0_21
.Lat_resc:
	s_nop 7
	s_nop 7
	v_mov_b32_e32 v242, v226
	v_mov_b32_e32 v243, v226
	s_nop 1
	v_permlane32_swap_b32_e32 v242, v243
	v_max_f32_e32 v242, v242, v243
	v_log_f32_e32 v242, v242
	s_nop 0
	v_max_f32_e32 v242, 0, v242
	v_exp_f32_e64 v243, -v242
	v_sub_f32_e32 v32, v32, v242
	v_sub_f32_e32 v33, v33, v242
	v_sub_f32_e32 v34, v34, v242
	v_sub_f32_e32 v35, v35, v242
	v_sub_f32_e32 v36, v36, v242
	v_sub_f32_e32 v37, v37, v242
	v_sub_f32_e32 v38, v38, v242
	v_sub_f32_e32 v39, v39, v242
	v_sub_f32_e32 v40, v40, v242
	v_sub_f32_e32 v41, v41, v242
	v_sub_f32_e32 v42, v42, v242
	v_sub_f32_e32 v43, v43, v242
	v_sub_f32_e32 v44, v44, v242
	v_sub_f32_e32 v45, v45, v242
	v_sub_f32_e32 v46, v46, v242
	v_sub_f32_e32 v47, v47, v242
	v_sub_f32_e32 v168, v168, v242
	v_sub_f32_e32 v169, v169, v242
	v_sub_f32_e32 v170, v170, v242
	v_sub_f32_e32 v171, v171, v242
	v_sub_f32_e32 v172, v172, v242
	v_sub_f32_e32 v173, v173, v242
	v_sub_f32_e32 v174, v174, v242
	v_sub_f32_e32 v175, v175, v242
	v_sub_f32_e32 v176, v176, v242
	v_sub_f32_e32 v177, v177, v242
	v_sub_f32_e32 v178, v178, v242
	v_sub_f32_e32 v179, v179, v242
	v_sub_f32_e32 v180, v180, v242
	v_sub_f32_e32 v181, v181, v242
	v_sub_f32_e32 v182, v182, v242
	v_sub_f32_e32 v183, v183, v242
	v_mul_f32_e32 v48, v48, v243
	v_mul_f32_e32 v49, v49, v243
	v_mul_f32_e32 v50, v50, v243
	v_mul_f32_e32 v51, v51, v243
	v_mul_f32_e32 v52, v52, v243
	v_mul_f32_e32 v53, v53, v243
	v_mul_f32_e32 v54, v54, v243
	v_mul_f32_e32 v55, v55, v243
	v_mul_f32_e32 v56, v56, v243
	v_mul_f32_e32 v57, v57, v243
	v_mul_f32_e32 v58, v58, v243
	v_mul_f32_e32 v59, v59, v243
	v_mul_f32_e32 v60, v60, v243
	v_mul_f32_e32 v61, v61, v243
	v_mul_f32_e32 v62, v62, v243
	v_mul_f32_e32 v63, v63, v243
	v_mul_f32_e32 v0, v0, v243
	v_mul_f32_e32 v1, v1, v243
	v_mul_f32_e32 v2, v2, v243
	v_mul_f32_e32 v3, v3, v243
	v_mul_f32_e32 v4, v4, v243
	v_mul_f32_e32 v5, v5, v243
	v_mul_f32_e32 v6, v6, v243
	v_mul_f32_e32 v7, v7, v243
	v_mul_f32_e32 v8, v8, v243
	v_mul_f32_e32 v9, v9, v243
	v_mul_f32_e32 v10, v10, v243
	v_mul_f32_e32 v11, v11, v243
	v_mul_f32_e32 v12, v12, v243
	v_mul_f32_e32 v13, v13, v243
	v_mul_f32_e32 v14, v14, v243
	v_mul_f32_e32 v15, v15, v243
	v_mul_f32_e32 v16, v16, v243
	v_mul_f32_e32 v17, v17, v243
	v_mul_f32_e32 v18, v18, v243
	v_mul_f32_e32 v19, v19, v243
	v_mul_f32_e32 v20, v20, v243
	v_mul_f32_e32 v21, v21, v243
	v_mul_f32_e32 v22, v22, v243
	v_mul_f32_e32 v23, v23, v243
	v_mul_f32_e32 v24, v24, v243
	v_mul_f32_e32 v25, v25, v243
	v_mul_f32_e32 v26, v26, v243
	v_mul_f32_e32 v27, v27, v243
	v_mul_f32_e32 v28, v28, v243
	v_mul_f32_e32 v29, v29, v243
	v_mul_f32_e32 v30, v30, v243
	v_mul_f32_e32 v31, v31, v243
	v_mul_f32_e32 v138, v138, v243
	v_cvt_pk_bf16_f32 v148, v48, v49
	v_cvt_pk_bf16_f32 v149, v50, v51
	v_cvt_pk_bf16_f32 v150, v52, v53
	v_cvt_pk_bf16_f32 v151, v54, v55
	v_cvt_pk_bf16_f32 v152, v56, v57
	v_cvt_pk_bf16_f32 v153, v58, v59
	v_cvt_pk_bf16_f32 v154, v60, v61
	v_cvt_pk_bf16_f32 v155, v62, v63
	s_branch .Lat_resc_back

.LBB0_238:
	s_andn2_b64 vcc, exec, s[24:25]
	s_cbranch_vccnz .LBB0_245
	s_lshl_b32 s24, s12, 9
	s_ashr_i32 s25, s24, 31
	s_lshl_b64 s[24:25], s[24:25], 2
	v_lshlrev_b32_e32 v25, 3, v204
	s_add_u32 s20, s20, s24
	v_and_b32_e32 v26, 56, v25
	s_addc_u32 s21, s21, s25
	v_lshlrev_b32_e32 v28, 2, v26
	v_mov_b32_e32 v29, v81
	v_lshl_add_u64 v[38:39], s[20:21], 0, v[28:29]
	s_movk_i32 s10, 0x110
	v_ashrrev_i32_e32 v28, 2, v204
	v_ashrrev_i32_e32 v24, 2, v24
	v_mad_u32_u24 v25, v26, s10, 0
	v_add_u32_e32 v27, 0, v140
	v_and_b32_e32 v28, -2, v28
	v_and_b32_e32 v24, -2, v24
	v_mul_u32_u24_e32 v29, 0x110, v142
	s_add_i32 s10, s70, s66
	v_or_b32_e32 v32, v32, v142
	v_lshlrev_b32_e32 v36, 2, v141
	v_lshl_add_u64 v[40:41], s[36:37], 0, v[80:81]
	s_lshl_b32 s24, s66, 4
	s_lshl_b32 s25, s70, 4
	s_lshl_b32 s35, s10, 6
	s_lshl_b32 s36, s66, 6
	v_add_u32_e32 v55, v25, v28
	v_add_u32_e32 v56, v25, v24
	v_lshlrev_b32_e32 v42, 1, v26
	v_add_u32_e32 v57, v27, v29
	s_mov_b32 s37, s70
	s_and_b64 vcc, exec, s[8:9]
	s_cbranch_vccnz .LBB0_241
	s_load_dwordx2 s[88:89], s[0:1], 0xc0
	s_and_b32 s90, s37, 7
	s_lshl_b32 s90, s90, 8
	s_mov_b32 s91, 0
	v_lshl_add_u64 v[78:79], v[38:39], 0, s[90:91]
	global_load_dwordx4 v[70:73], v[78:79], off offset:16
	global_load_dwordx4 v[74:77], v[78:79], off
	s_waitcnt lgkmcnt(0)
	s_branch .Lsp_241

.Lsp_241:
	s_and_b32 s10, s25, 0xffffff80
	s_and_b32 s38, s37, 7
	v_add_u32_e32 v52, s10, v32
	v_mov_b64_e32 v[24:25], s[4:5]
	s_movk_i32 s10, 0xe00
	v_mad_i64_i32 v[24:25], s[20:21], v52, s10, v[24:25]
	s_lshl_b32 s10, s38, 7
	v_lshl_add_u64 v[24:25], v[24:25], 0, s[10:11]
	v_lshlrev_b32_e32 v80, 1, v36
	v_lshl_add_u64 v[24:25], v[24:25], 0, v[80:81]
	global_load_dwordx2 v[50:51], v[24:25], off offset:1536
	global_load_dwordx2 v[48:49], v[24:25], off offset:1568
	global_load_dwordx2 v[46:47], v[24:25], off offset:1600
	global_load_dwordx2 v[44:45], v[24:25], off offset:1632
	s_nop 0
	s_nop 0
	s_waitcnt vmcnt(4)
	v_lshlrev_b32_e32 v53, 16, v0
	v_mul_f32_e32 v53, v54, v53
	s_add_i32 s37, s37, s66
	s_cmpk_gt_i32 s37, 0x5ff
	s_cselect_b64 s[20:21], -1, 0
	s_and_b64 vcc, exec, s[20:21]
	v_mul_f32_e32 v53, v53, v74
	v_cvt_pk_bf16_f32 v53, v53, s0
	ds_write_b16 v55, v53
	v_and_b32_e32 v53, 0xffff0000, v0
	v_mul_f32_e32 v53, v54, v53
	v_mul_f32_e32 v53, v53, v75
	v_cvt_pk_bf16_f32 v53, v53, s0
	ds_write_b16 v55, v53 offset:272
	v_lshlrev_b32_e32 v53, 16, v1
	v_mul_f32_e32 v53, v54, v53
	v_mul_f32_e32 v53, v53, v76
	v_cvt_pk_bf16_f32 v53, v53, s0
	ds_write_b16 v55, v53 offset:544
	v_and_b32_e32 v53, 0xffff0000, v1
	v_mul_f32_e32 v53, v54, v53
	v_mul_f32_e32 v53, v53, v77
	v_cvt_pk_bf16_f32 v53, v53, s0
	ds_write_b16 v55, v53 offset:816
	v_lshlrev_b32_e32 v53, 16, v2
	v_mul_f32_e32 v53, v54, v53
	v_mul_f32_e32 v53, v53, v70
	v_cvt_pk_bf16_f32 v53, v53, s0
	ds_write_b16 v55, v53 offset:1088
	v_and_b32_e32 v53, 0xffff0000, v2
	v_mul_f32_e32 v53, v54, v53
	v_mul_f32_e32 v53, v53, v71
	v_cvt_pk_bf16_f32 v53, v53, s0
	ds_write_b16 v55, v53 offset:1360
	v_lshlrev_b32_e32 v53, 16, v3
	v_mul_f32_e32 v53, v54, v53
	v_mul_f32_e32 v53, v53, v72
	v_cvt_pk_bf16_f32 v53, v53, s0
	ds_write_b16 v55, v53 offset:1632
	v_and_b32_e32 v53, 0xffff0000, v3
	v_mul_f32_e32 v53, v54, v53
	v_mul_f32_e32 v53, v53, v73
	v_cvt_pk_bf16_f32 v53, v53, s0
	ds_write_b16 v55, v53 offset:1904
	v_lshlrev_b32_e32 v53, 16, v4
	v_mul_f32_e32 v53, v43, v53
	v_mul_f32_e32 v28, v53, v74
	v_cvt_pk_bf16_f32 v28, v28, s0
	ds_write_b16 v56, v28
	v_and_b32_e32 v28, 0xffff0000, v4
	v_mul_f32_e32 v28, v43, v28
	v_mul_f32_e32 v28, v28, v75
	v_cvt_pk_bf16_f32 v28, v28, s0
	ds_write_b16 v56, v28 offset:272
	v_lshlrev_b32_e32 v28, 16, v5
	v_mul_f32_e32 v28, v43, v28
	v_mul_f32_e32 v28, v28, v76
	v_cvt_pk_bf16_f32 v28, v28, s0
	ds_write_b16 v56, v28 offset:544
	v_and_b32_e32 v28, 0xffff0000, v5
	v_mul_f32_e32 v28, v43, v28
	v_mul_f32_e32 v28, v28, v77
	v_cvt_pk_bf16_f32 v28, v28, s0
	ds_write_b16 v56, v28 offset:816
	v_lshlrev_b32_e32 v28, 16, v6
	v_mul_f32_e32 v28, v43, v28
	v_mul_f32_e32 v24, v28, v70
	v_cvt_pk_bf16_f32 v24, v24, s0
	ds_write_b16 v56, v24 offset:1088
	v_and_b32_e32 v24, 0xffff0000, v6
	v_mul_f32_e32 v24, v43, v24
	v_mul_f32_e32 v24, v24, v71
	v_cvt_pk_bf16_f32 v24, v24, s0
	ds_write_b16 v56, v24 offset:1360
	v_lshlrev_b32_e32 v24, 16, v7
	v_mul_f32_e32 v24, v43, v24
	v_mul_f32_e32 v24, v24, v72
	v_cvt_pk_bf16_f32 v24, v24, s0
	ds_write_b16 v56, v24 offset:1632
	v_and_b32_e32 v24, 0xffff0000, v7
	v_mul_f32_e32 v24, v43, v24
	v_mul_f32_e32 v24, v24, v73
	v_cvt_pk_bf16_f32 v24, v24, s0
	ds_write_b16 v56, v24 offset:1904
	s_waitcnt lgkmcnt(0)
	s_barrier
	s_cbranch_vccnz .Lsp_243
	s_add_i32 s39, s24, s25
	s_and_b32 s39, s39, 0xffffff80
	v_add_u32_e32 v0, s39, v35
	v_mov_b64_e32 v[4:5], s[4:5]
	s_movk_i32 s43, 0xe00
	s_and_b32 s42, s35, 0x1c0
	v_mad_i64_i32 v[2:3], s[40:41], v0, s43, v[4:5]
	s_lshl_b32 s40, s42, 1
	s_mov_b32 s41, s11
	v_ashrrev_i32_e32 v1, 31, v0
	v_lshl_add_u64 v[2:3], v[2:3], 0, s[40:41]
	v_mov_b32_e32 v43, v81
	v_lshl_add_u64 v[2:3], v[2:3], 0, v[42:43]
	v_lshl_add_u64 v[6:7], v[0:1], 2, s[2:3]
	global_load_dwordx4 v[0:3], v[2:3], off offset:2560
	s_nop 0
	global_load_dword v54, v[6:7], off
	v_add_u32_e32 v6, s39, v37
	v_mad_i64_i32 v[4:5], s[42:43], v6, s43, v[4:5]
	v_lshl_add_u64 v[4:5], v[4:5], 0, s[40:41]
	v_ashrrev_i32_e32 v7, 31, v6
	v_lshl_add_u64 v[4:5], v[4:5], 0, v[42:43]
	v_lshl_add_u64 v[24:25], v[6:7], 2, s[2:3]
	global_load_dwordx4 v[4:7], v[4:5], off offset:2560
	s_nop 0
	global_load_dword v43, v[24:25], off
.Lsp_243:
	s_lshl_b32 s86, s38, 6
	ds_read_b128 v[82:85], v57
	ds_read_b128 v[86:89], v57 offset:64
	ds_read_b128 v[90:93], v57 offset:4352
	ds_read_b128 v[94:97], v57 offset:4416
	ds_read_b128 v[98:101], v57 offset:8704
	ds_read_b128 v[102:105], v57 offset:8768
	ds_read_b128 v[106:109], v57 offset:13056
	ds_read_b128 v[110:113], v57 offset:13120
	v_ashrrev_i32_e32 v53, 31, v52
	v_lshlrev_b64 v[52:53], 11, v[52:53]
	s_add_i32 s25, s25, s24
	v_lshl_add_u64 v[52:53], s[88:89], 0, v[52:53]
	s_add_i32 s35, s35, s36
	s_waitcnt lgkmcnt(7)
	v_mfma_f32_16x16x32_bf16 v[24:27], v[82:85], v[8:11], 0
	ds_read_b128 v[114:117], v57 offset:128
	s_waitcnt lgkmcnt(7)
	v_mfma_f32_16x16x32_bf16 v[24:27], v[86:89], v[12:15], v[24:27]
	ds_read_b128 v[118:121], v57 offset:4480
	s_waitcnt lgkmcnt(7)
	v_mfma_f32_16x16x32_bf16 v[28:31], v[90:93], v[8:11], 0
	ds_read_b128 v[122:125], v57 offset:8832
	s_waitcnt lgkmcnt(7)
	v_mfma_f32_16x16x32_bf16 v[28:31], v[94:97], v[12:15], v[28:31]
	ds_read_b128 v[126:129], v57 offset:13184
	s_waitcnt lgkmcnt(7)
	v_mfma_f32_16x16x32_bf16 v[58:61], v[98:101], v[8:11], 0
	ds_read_b128 v[130:133], v57 offset:192
	s_waitcnt lgkmcnt(7)
	v_mfma_f32_16x16x32_bf16 v[58:61], v[102:105], v[12:15], v[58:61]
	ds_read_b128 v[134:137], v57 offset:4544
	s_waitcnt lgkmcnt(7)
	v_mfma_f32_16x16x32_bf16 v[62:65], v[106:109], v[8:11], 0
	ds_read_b128 v[150:153], v57 offset:8896
	s_waitcnt lgkmcnt(7)
	v_mfma_f32_16x16x32_bf16 v[62:65], v[110:113], v[12:15], v[62:65]
	ds_read_b128 v[154:157], v57 offset:13248
	s_waitcnt lgkmcnt(7)
	v_mfma_f32_16x16x32_bf16 v[24:27], v[114:117], v[16:19], v[24:27]
	s_waitcnt lgkmcnt(6)
	v_mfma_f32_16x16x32_bf16 v[28:31], v[118:121], v[16:19], v[28:31]
	s_waitcnt lgkmcnt(5)
	v_mfma_f32_16x16x32_bf16 v[58:61], v[122:125], v[16:19], v[58:61]
	s_waitcnt lgkmcnt(4)
	v_mfma_f32_16x16x32_bf16 v[62:65], v[126:129], v[16:19], v[62:65]
	s_waitcnt lgkmcnt(3)
	v_mfma_f32_16x16x32_bf16 v[24:27], v[130:133], v[20:23], v[24:27]
	s_waitcnt lgkmcnt(2)
	v_mfma_f32_16x16x32_bf16 v[28:31], v[134:137], v[20:23], v[28:31]
	s_waitcnt lgkmcnt(1)
	v_mfma_f32_16x16x32_bf16 v[58:61], v[150:153], v[20:23], v[58:61]
	s_waitcnt lgkmcnt(0)
	v_mfma_f32_16x16x32_bf16 v[62:65], v[154:157], v[20:23], v[62:65]
	s_and_b64 vcc, exec, s[20:21]
	s_cbranch_vccnz .Lsp_last
	s_waitcnt vmcnt(4)
	s_branch .Lsp_epi

.Lsp_epi:
	s_nop 7
	v_pk_add_f32 v[24:25], v[34:35], v[24:25] op_sel_hi:[0,1]
	v_pk_add_f32 v[26:27], v[34:35], v[26:27] op_sel_hi:[0,1]
	v_pk_add_f32 v[28:29], v[34:35], v[28:29] op_sel_hi:[0,1]
	v_pk_add_f32 v[30:31], v[34:35], v[30:31] op_sel_hi:[0,1]
	v_or_b32_e32 v68, s86, v36
	v_lshlrev_b32_e32 v66, 16, v50
	v_and_b32_e32 v67, 0xffff0000, v50
	v_lshlrev_b32_e32 v50, 16, v51
	v_and_b32_e32 v51, 0xffff0000, v51
	v_pk_mul_f32 v[24:25], v[24:25], v[66:67]
	v_pk_mul_f32 v[26:27], v[26:27], v[50:51]
	v_lshlrev_b32_e32 v80, 1, v68
	v_cvt_pk_bf16_f32 v24, v24, v25
	v_cvt_pk_bf16_f32 v25, v26, v27
	v_lshl_add_u64 v[26:27], v[52:53], 0, v[80:81]
	global_store_dwordx2 v[26:27], v[24:25], off offset:1024
	v_lshlrev_b32_e32 v24, 16, v48
	v_and_b32_e32 v25, 0xffff0000, v48
	v_pk_mul_f32 v[24:25], v[28:29], v[24:25]
	v_lshlrev_b32_e32 v28, 16, v49
	v_and_b32_e32 v29, 0xffff0000, v49
	v_pk_mul_f32 v[28:29], v[30:31], v[28:29]
	v_cvt_pk_bf16_f32 v24, v24, v25
	v_cvt_pk_bf16_f32 v25, v28, v29
	global_store_dwordx2 v[26:27], v[24:25], off offset:1056
	v_lshlrev_b32_e32 v24, 16, v46
	v_and_b32_e32 v25, 0xffff0000, v46
	v_pk_add_f32 v[28:29], v[34:35], v[58:59] op_sel_hi:[0,1]
	v_pk_mul_f32 v[24:25], v[28:29], v[24:25]
	v_lshlrev_b32_e32 v28, 16, v47
	v_and_b32_e32 v29, 0xffff0000, v47
	v_pk_add_f32 v[30:31], v[34:35], v[60:61] op_sel_hi:[0,1]
	v_pk_mul_f32 v[28:29], v[30:31], v[28:29]
	v_cvt_pk_bf16_f32 v24, v24, v25
	v_cvt_pk_bf16_f32 v25, v28, v29
	global_store_dwordx2 v[26:27], v[24:25], off offset:1088
	v_lshlrev_b32_e32 v24, 16, v44
	v_and_b32_e32 v25, 0xffff0000, v44
	v_pk_add_f32 v[28:29], v[34:35], v[62:63] op_sel_hi:[0,1]
	v_pk_mul_f32 v[24:25], v[28:29], v[24:25]
	v_lshlrev_b32_e32 v28, 16, v45
	v_and_b32_e32 v29, 0xffff0000, v45
	v_pk_add_f32 v[30:31], v[34:35], v[64:65] op_sel_hi:[0,1]
	v_pk_mul_f32 v[28:29], v[30:31], v[28:29]
	v_cvt_pk_bf16_f32 v24, v24, v25
	v_cvt_pk_bf16_f32 v25, v28, v29
	global_store_dwordx2 v[26:27], v[24:25], off offset:1120
	s_and_b64 vcc, exec, s[20:21]
	s_barrier
	s_cbranch_vccnz .LBB0_245
	s_branch .Lsp_241
